# all residual-add GEMM epilogues (FFN down projections and mixer output projection): counted vmcnt waits in front of the first use of each load instead of vmcnt(0) per round
# baseline (speedup 1.0000x reference)
;     __device__ __forceinline__ void operator()(const f32x4 (&acc)[2][2][4][2], const pg8::Unit& u, int wr, int wc, int fr, int fq) const {
;         const int row0 = u.pm * 256 + wr * 64 + fr, col0 = u.pn * 256 + wc * 32 + 4 * fq;
; #pragma unroll
;         for (int ai = 0; ai < 2; ++ai)
; #pragma unroll
;             for (int mh = 0; mh < 2; ++mh) {
;                 f32x4 xi[2][2][2];
; #pragma unroll
;                 for (int m = 0; m < 2; ++m)
; #pragma unroll
;                     for (int bj = 0; bj < 2; ++bj)
; #pragma unroll
;                         for (int n = 0; n < 2; ++n) xi[m][bj][n] = *(const f32x4*)(Xin + (size_t)(row0 + ai * 128 + (2 * mh + m) * 16) * D + col0 + bj * 128 + n * 16);
;                 __builtin_amdgcn_sched_barrier(0);
; #pragma unroll
;                 for (int m = 0; m < 2; ++m)
; #pragma unroll
;                     for (int bj = 0; bj < 2; ++bj)
; #pragma unroll
;                         for (int n = 0; n < 2; ++n) *(f32x4*)(Xout + (size_t)(row0 + ai * 128 + (2 * mh + m) * 16) * D + col0 + bj * 128 + n * 16) = xi[m][bj][n] + acc[ai][bj][2 * mh + m][n] * scale;
.LBB0_121:
	v_lshl_or_b32 v16, s30, 8, v148
	v_lshl_add_u32 v26, s31, 8, v146
	v_ashrrev_i32_e32 v17, 31, v16
	v_readlane_b32 s2, v254, 52
	v_lshlrev_b64 v[16:17], 2, v[16:17]
	v_readlane_b32 s3, v254, 53
	v_ashrrev_i32_e32 v27, 31, v26
	v_lshlrev_b64 v[24:25], 12, v[26:27]
	v_lshl_add_u64 v[18:19], s[2:3], 0, v[16:17]
	v_lshl_add_u64 v[150:151], v[18:19], 0, v[24:25]
	global_load_dwordx4 v[40:43], v[150:151], off
	global_load_dwordx4 v[168:171], v[150:151], off offset:64
	global_load_dwordx4 v[172:175], v[150:151], off offset:512
	global_load_dwordx4 v[176:179], v[150:151], off offset:576
	v_or_b32_e32 v150, 16, v26
	v_ashrrev_i32_e32 v151, 31, v150
	v_lshlrev_b64 v[150:151], 12, v[150:151]
	v_lshl_add_u64 v[158:159], v[18:19], 0, v[150:151]
	global_load_dwordx4 v[180:183], v[158:159], off
	global_load_dwordx4 v[184:187], v[158:159], off offset:64
	global_load_dwordx4 v[188:191], v[158:159], off offset:512
	global_load_dwordx4 v[192:195], v[158:159], off offset:576
	s_waitcnt vmcnt(7)
	v_pk_add_f32 v[42:43], v[134:135], v[42:43]
	v_lshl_add_u64 v[134:135], s[2:3], 0, v[24:25]
	v_pk_add_f32 v[40:41], v[136:137], v[40:41]
	v_lshl_add_u64 v[134:135], v[134:135], 0, v[16:17]
	global_store_dwordx4 v[134:135], v[40:43], off
	s_nop 1
	s_waitcnt vmcnt(7)
	v_pk_add_f32 v[42:43], v[126:127], v[170:171]
	v_pk_add_f32 v[40:41], v[124:125], v[168:169]
	global_store_dwordx4 v[134:135], v[40:43], off offset:64
	s_nop 1
	s_waitcnt vmcnt(7)
	v_pk_add_f32 v[42:43], v[144:145], v[174:175]
	v_pk_add_f32 v[40:41], v[142:143], v[172:173]
	global_store_dwordx4 v[134:135], v[40:43], off offset:512
	s_nop 1
	s_waitcnt vmcnt(7)
	v_pk_add_f32 v[42:43], v[140:141], v[178:179]
	v_pk_add_f32 v[40:41], v[138:139], v[176:177]
	global_store_dwordx4 v[134:135], v[40:43], off offset:576
	s_nop 1
	s_waitcnt vmcnt(7)
	v_pk_add_f32 v[40:41], v[116:117], v[180:181]
	v_lshl_add_u64 v[116:117], s[2:3], 0, v[150:151]
	v_pk_add_f32 v[42:43], v[118:119], v[182:183]
	v_lshl_add_u64 v[116:117], v[116:117], 0, v[16:17]
	global_store_dwordx4 v[116:117], v[40:43], off
	s_nop 1
	s_waitcnt vmcnt(7)
	v_pk_add_f32 v[42:43], v[110:111], v[186:187]
	v_pk_add_f32 v[40:41], v[108:109], v[184:185]
	global_store_dwordx4 v[116:117], v[40:43], off offset:64
	s_nop 1
	s_waitcnt vmcnt(7)
	v_pk_add_f32 v[42:43], v[122:123], v[190:191]
	v_pk_add_f32 v[40:41], v[120:121], v[188:189]
	global_store_dwordx4 v[116:117], v[40:43], off offset:512
	s_nop 1
	s_waitcnt vmcnt(7)
	v_pk_add_f32 v[42:43], v[114:115], v[194:195]
	v_pk_add_f32 v[40:41], v[112:113], v[192:193]
	global_store_dwordx4 v[116:117], v[40:43], off offset:576
	s_nop 1
	v_or_b32_e32 v40, 32, v26
	v_or_b32_e32 v26, 48, v26
	v_ashrrev_i32_e32 v41, 31, v40
	v_ashrrev_i32_e32 v27, 31, v26
	v_lshlrev_b64 v[142:143], 12, v[40:41]
	v_lshlrev_b64 v[26:27], 12, v[26:27]
	v_lshl_add_u64 v[116:117], v[18:19], 0, v[142:143]
	v_lshl_add_u64 v[138:139], v[18:19], 0, v[26:27]
	global_load_dwordx4 v[40:43], v[116:117], off
	global_load_dwordx4 v[108:111], v[116:117], off offset:64
	global_load_dwordx4 v[112:115], v[116:117], off offset:512
	s_nop 0
	global_load_dwordx4 v[116:119], v[116:117], off offset:576
	s_nop 0
	global_load_dwordx4 v[120:123], v[138:139], off
	global_load_dwordx4 v[124:127], v[138:139], off offset:64
	global_load_dwordx4 v[134:137], v[138:139], off offset:512
	s_nop 0
	global_load_dwordx4 v[138:141], v[138:139], off offset:576
	s_waitcnt vmcnt(7)
	v_pk_add_f32 v[40:41], v[100:101], v[40:41]
	v_lshl_add_u64 v[100:101], s[2:3], 0, v[142:143]
	v_pk_add_f32 v[42:43], v[102:103], v[42:43]
	v_lshl_add_u64 v[100:101], v[100:101], 0, v[16:17]
	global_store_dwordx4 v[100:101], v[40:43], off
	v_lshl_add_u64 v[26:27], s[2:3], 0, v[26:27]
	v_lshl_add_u64 v[26:27], v[26:27], 0, v[16:17]
	s_waitcnt vmcnt(7)
	v_pk_add_f32 v[42:43], v[94:95], v[110:111]
	v_pk_add_f32 v[40:41], v[92:93], v[108:109]
	global_store_dwordx4 v[100:101], v[40:43], off offset:64
	s_nop 1
	s_waitcnt vmcnt(7)
	v_pk_add_f32 v[42:43], v[106:107], v[114:115]
	v_pk_add_f32 v[40:41], v[104:105], v[112:113]
	global_store_dwordx4 v[100:101], v[40:43], off offset:512
	s_nop 1
	s_waitcnt vmcnt(7)
	v_pk_add_f32 v[42:43], v[98:99], v[118:119]
	v_pk_add_f32 v[40:41], v[96:97], v[116:117]
	global_store_dwordx4 v[100:101], v[40:43], off offset:576
	s_nop 1
	s_waitcnt vmcnt(7)
	v_pk_add_f32 v[42:43], v[86:87], v[122:123]
	v_pk_add_f32 v[40:41], v[84:85], v[120:121]
	global_store_dwordx4 v[26:27], v[40:43], off
	s_nop 1
	s_waitcnt vmcnt(7)
	v_pk_add_f32 v[42:43], v[74:75], v[126:127]
	v_pk_add_f32 v[40:41], v[72:73], v[124:125]
	global_store_dwordx4 v[26:27], v[40:43], off offset:64
	s_nop 1
	s_waitcnt vmcnt(7)
	v_pk_add_f32 v[42:43], v[90:91], v[136:137]
	v_pk_add_f32 v[40:41], v[88:89], v[134:135]
	global_store_dwordx4 v[26:27], v[40:43], off offset:512
	s_nop 1
	s_waitcnt vmcnt(7)
; #define PG8_BAR __builtin_amdgcn_s_barrier()
; template <class Epi, class Sched, bool ALIGN_EPI = false, bool SP2 = false>
; __device__ __forceinline__ void gemm_phase(PG8_LAS unsigned char* lds, const Gemm g, const Sched& S, const Epi& E) {
;     ...
;         if constexpr (ALIGN_EPI) { if (wr == 0) PG8_BAR; }
;         if constexpr (!Epi::AFTER_DRAIN) { E(acc, cur, wr, wc, fr, fq); S.done(cur); }
;         if (!has_next) break;
; #pragma unroll
;         for (int a = 0; a < 2; ++a)
; #pragma unroll
;             for (int b = 0; b < 2; ++b)
; #pragma unroll
;                 for (int m = 0; m < 4; ++m)
; #pragma unroll
;                     for (int n = 0; n < 2; ++n) acc[a][b][m][n] = (f32x4){0.f, 0.f, 0.f, 0.f};
;         cur = nxt; cA = nA; cB = nB; ++ui;
;         if constexpr (ALIGN_EPI) { if (wr == 1) PG8_BAR; }
;     __device__ __forceinline__ void operator()(const f32x4 (&acc)[2][2][4][2], const pg8::Unit& u, int wr, int wc, int fr, int fq) const {
;     ...
;         for (int ai = 0; ai < 2; ++ai)
; #pragma unroll
;             for (int mh = 0; mh < 2; ++mh) {
;                 f32x4 xi[2][2][2];
; #pragma unroll
;                 for (int m = 0; m < 2; ++m)
; #pragma unroll
;                     for (int bj = 0; bj < 2; ++bj)
; #pragma unroll
;                         for (int n = 0; n < 2; ++n) xi[m][bj][n] = *(const f32x4*)(Xin + (size_t)(row0 + ai * 128 + (2 * mh + m) * 16) * D + col0 + bj * 128 + n * 16);
;                 __builtin_amdgcn_sched_barrier(0);
; #pragma unroll
;                 for (int m = 0; m < 2; ++m)
; #pragma unroll
;                     for (int bj = 0; bj < 2; ++bj)
; #pragma unroll
;                         for (int n = 0; n < 2; ++n) *(f32x4*)(Xout + (size_t)(row0 + ai * 128 + (2 * mh + m) * 16) * D + col0 + bj * 128 + n * 16) = xi[m][bj][n] + acc[ai][bj][2 * mh + m][n] * scale;
;                 __builtin_amdgcn_sched_barrier(0);
;             }
	v_pk_add_f32 v[42:43], v[82:83], v[140:141]
	v_pk_add_f32 v[40:41], v[80:81], v[138:139]
	global_store_dwordx4 v[26:27], v[40:43], off offset:576
	s_mov_b64 s[0:1], 0x80000
	v_lshl_add_u64 v[26:27], v[24:25], 0, s[0:1]
	s_mov_b64 s[0:1], 0x90000
	v_lshl_add_u64 v[104:105], v[24:25], 0, s[0:1]
	v_lshl_add_u64 v[84:85], v[18:19], 0, v[26:27]
	v_lshl_add_u64 v[100:101], v[18:19], 0, v[104:105]
	global_load_dwordx4 v[40:43], v[84:85], off
	global_load_dwordx4 v[72:75], v[84:85], off offset:64
	global_load_dwordx4 v[80:83], v[84:85], off offset:512
	s_nop 0
	global_load_dwordx4 v[84:87], v[84:85], off offset:576
	s_nop 0
	global_load_dwordx4 v[88:91], v[100:101], off
	global_load_dwordx4 v[92:95], v[100:101], off offset:64
	global_load_dwordx4 v[96:99], v[100:101], off offset:512
	s_nop 0
	global_load_dwordx4 v[100:103], v[100:101], off offset:576
	v_lshl_add_u64 v[26:27], s[2:3], 0, v[26:27]
	s_waitcnt vmcnt(7)
	v_pk_add_f32 v[42:43], v[66:67], v[42:43]
	v_pk_add_f32 v[40:41], v[64:65], v[40:41]
	v_lshl_add_u64 v[26:27], v[26:27], 0, v[16:17]
	global_store_dwordx4 v[26:27], v[40:43], off
	s_nop 1
	s_waitcnt vmcnt(7)
	v_pk_add_f32 v[42:43], v[62:63], v[74:75]
	v_pk_add_f32 v[40:41], v[60:61], v[72:73]
	global_store_dwordx4 v[26:27], v[40:43], off offset:64
	s_nop 1
	s_waitcnt vmcnt(7)
	v_pk_add_f32 v[42:43], v[78:79], v[82:83]
	v_pk_add_f32 v[40:41], v[76:77], v[80:81]
	global_store_dwordx4 v[26:27], v[40:43], off offset:512
	s_nop 1
	s_waitcnt vmcnt(7)
	v_pk_add_f32 v[42:43], v[70:71], v[86:87]
	v_pk_add_f32 v[40:41], v[68:69], v[84:85]
	global_store_dwordx4 v[26:27], v[40:43], off offset:576
	v_lshl_add_u64 v[26:27], s[2:3], 0, v[104:105]
	v_lshl_add_u64 v[26:27], v[26:27], 0, v[16:17]
	s_waitcnt vmcnt(7)
	v_pk_add_f32 v[42:43], v[54:55], v[90:91]
	v_pk_add_f32 v[40:41], v[52:53], v[88:89]
	global_store_dwordx4 v[26:27], v[40:43], off
	s_nop 1
	s_waitcnt vmcnt(7)
	v_pk_add_f32 v[42:43], v[46:47], v[94:95]
	v_pk_add_f32 v[40:41], v[44:45], v[92:93]
	global_store_dwordx4 v[26:27], v[40:43], off offset:64
	s_nop 1
	s_waitcnt vmcnt(7)
	v_pk_add_f32 v[42:43], v[58:59], v[98:99]
	v_pk_add_f32 v[40:41], v[56:57], v[96:97]
	global_store_dwordx4 v[26:27], v[40:43], off offset:512
	s_nop 1
	s_waitcnt vmcnt(7)
	v_pk_add_f32 v[42:43], v[50:51], v[102:103]
	v_pk_add_f32 v[40:41], v[48:49], v[100:101]
	global_store_dwordx4 v[26:27], v[40:43], off offset:576
	s_mov_b64 s[0:1], 0xa0000
	v_lshl_add_u64 v[68:69], v[24:25], 0, s[0:1]
	s_mov_b64 s[0:1], 0xb0000
	v_lshl_add_u64 v[70:71], v[24:25], 0, s[0:1]
	v_lshl_add_u64 v[26:27], v[18:19], 0, v[68:69]
	v_lshl_add_u64 v[18:19], v[18:19], 0, v[70:71]
	global_load_dwordx4 v[40:43], v[26:27], off
	global_load_dwordx4 v[44:47], v[26:27], off offset:64
	global_load_dwordx4 v[48:51], v[26:27], off offset:512
	global_load_dwordx4 v[52:55], v[26:27], off offset:576
	s_nop 0
	global_load_dwordx4 v[24:27], v[18:19], off
	global_load_dwordx4 v[56:59], v[18:19], off offset:64
	global_load_dwordx4 v[60:63], v[18:19], off offset:512
	global_load_dwordx4 v[64:67], v[18:19], off offset:576
	v_lshl_add_u64 v[18:19], s[2:3], 0, v[68:69]
	s_waitcnt vmcnt(7)
	v_pk_add_f32 v[28:29], v[28:29], v[40:41]
	v_lshl_add_u64 v[40:41], v[18:19], 0, v[16:17]
	s_waitcnt vmcnt(6)
	v_pk_add_f32 v[22:23], v[22:23], v[46:47]
	v_pk_add_f32 v[20:21], v[20:21], v[44:45]
	global_store_dwordx4 v[40:41], v[20:23], off offset:64
	s_waitcnt vmcnt(6)
	v_pk_add_f32 v[18:19], v[36:37], v[48:49]
	v_pk_add_f32 v[30:31], v[30:31], v[42:43]
	v_pk_add_f32 v[20:21], v[38:39], v[50:51]
	global_store_dwordx4 v[40:41], v[18:21], off offset:512
	s_waitcnt vmcnt(5)
	v_pk_add_f32 v[14:15], v[14:15], v[26:27]
	v_pk_add_f32 v[12:13], v[12:13], v[24:25]
	v_pk_add_f32 v[20:21], v[34:35], v[54:55]
	v_pk_add_f32 v[18:19], v[32:33], v[52:53]
	global_store_dwordx4 v[40:41], v[18:21], off offset:576
	s_waitcnt vmcnt(5)
	v_pk_add_f32 v[10:11], v[10:11], v[58:59]
	v_pk_add_f32 v[8:9], v[8:9], v[56:57]
	v_lshl_add_u64 v[18:19], s[2:3], 0, v[70:71]
	v_lshl_add_u64 v[16:17], v[18:19], 0, v[16:17]
	s_waitcnt vmcnt(4)
	v_pk_add_f32 v[6:7], v[6:7], v[62:63]
	v_pk_add_f32 v[4:5], v[4:5], v[60:61]
	s_waitcnt vmcnt(3)
	v_pk_add_f32 v[2:3], v[2:3], v[66:67]
	v_pk_add_f32 v[0:1], v[0:1], v[64:65]
	global_store_dwordx4 v[40:41], v[28:31], off
	global_store_dwordx4 v[16:17], v[12:15], off
	global_store_dwordx4 v[16:17], v[8:11], off offset:64
	global_store_dwordx4 v[16:17], v[4:7], off offset:512
	global_store_dwordx4 v[16:17], v[0:3], off offset:576
	s_and_b64 vcc, exec, s[4:5]
	s_mov_b64 s[0:1], -1
	s_cbranch_vccnz .LBB0_104
	s_andn2_b64 vcc, exec, s[16:17]
	s_cbranch_vccnz .LBB0_103
	s_barrier
	s_branch .LBB0_103

;     __device__ __forceinline__ void operator()(const f32x4 (&acc)[2][2][4][2], const pg8::Unit& u, int wr, int wc, int fr, int fq) const {
;         const int row0 = u.pm * 256 + wr * 64 + fr, col0 = u.pn * 256 + wc * 32 + 4 * fq;
; #pragma unroll
;         for (int ai = 0; ai < 2; ++ai)
; #pragma unroll
;             for (int mh = 0; mh < 2; ++mh) {
;                 f32x4 xi[2][2][2];
; #pragma unroll
;                 for (int m = 0; m < 2; ++m)
; #pragma unroll
;                     for (int bj = 0; bj < 2; ++bj)
; #pragma unroll
;                         for (int n = 0; n < 2; ++n) xi[m][bj][n] = *(const f32x4*)(Xin + (size_t)(row0 + ai * 128 + (2 * mh + m) * 16) * D + col0 + bj * 128 + n * 16);
;                 __builtin_amdgcn_sched_barrier(0);
; #pragma unroll
;                 for (int m = 0; m < 2; ++m)
; #pragma unroll
;                     for (int bj = 0; bj < 2; ++bj)
; #pragma unroll
;                         for (int n = 0; n < 2; ++n) *(f32x4*)(Xout + (size_t)(row0 + ai * 128 + (2 * mh + m) * 16) * D + col0 + bj * 128 + n * 16) = xi[m][bj][n] + acc[ai][bj][2 * mh + m][n] * scale;
.LBB0_161:
	v_lshl_add_u32 v184, s35, 8, v140
	v_lshl_or_b32 v134, s34, 8, v142
	v_ashrrev_i32_e32 v135, 31, v134
	v_readlane_b32 s2, v254, 52
	v_or_b32_e32 v168, 16, v184
	v_lshlrev_b64 v[134:135], 2, v[134:135]
	v_readlane_b32 s3, v254, 53
	v_ashrrev_i32_e32 v185, 31, v184
	v_ashrrev_i32_e32 v169, 31, v168
	v_lshl_add_u64 v[136:137], s[2:3], 0, v[134:135]
	v_lshlrev_b64 v[138:139], 12, v[184:185]
	v_lshlrev_b64 v[186:187], 12, v[168:169]
	v_lshl_add_u64 v[162:163], v[136:137], 0, v[138:139]
	v_lshl_add_u64 v[180:181], v[136:137], 0, v[186:187]
	global_load_dwordx4 v[144:147], v[162:163], off
	global_load_dwordx4 v[148:151], v[162:163], off offset:64
	global_load_dwordx4 v[158:161], v[162:163], off offset:512
	s_nop 0
	global_load_dwordx4 v[162:165], v[162:163], off offset:576
	s_nop 0
	global_load_dwordx4 v[168:171], v[180:181], off
	global_load_dwordx4 v[172:175], v[180:181], off offset:64
	global_load_dwordx4 v[176:179], v[180:181], off offset:512
	s_nop 0
	global_load_dwordx4 v[180:183], v[180:181], off offset:576
	s_waitcnt vmcnt(7)
	v_pk_add_f32 v[124:125], v[124:125], v[144:145]
	v_lshl_add_u64 v[144:145], s[2:3], 0, v[138:139]
	v_lshl_add_u64 v[144:145], v[144:145], 0, v[134:135]
	s_waitcnt vmcnt(4)
	v_pk_add_f32 v[114:115], v[114:115], v[164:165]
	v_pk_add_f32 v[112:113], v[112:113], v[162:163]
	global_store_dwordx4 v[144:145], v[112:115], off offset:576
	v_pk_add_f32 v[126:127], v[126:127], v[146:147]
	v_pk_add_f32 v[122:123], v[122:123], v[150:151]
	v_lshl_add_u64 v[112:113], s[2:3], 0, v[186:187]
	v_pk_add_f32 v[120:121], v[120:121], v[148:149]
	v_pk_add_f32 v[118:119], v[118:119], v[160:161]
	v_pk_add_f32 v[116:117], v[116:117], v[158:159]
	s_waitcnt vmcnt(4)
	v_pk_add_f32 v[110:111], v[110:111], v[170:171]
	v_pk_add_f32 v[108:109], v[108:109], v[168:169]
	v_lshl_add_u64 v[112:113], v[112:113], 0, v[134:135]
	s_waitcnt vmcnt(3)
	v_pk_add_f32 v[106:107], v[106:107], v[174:175]
	v_pk_add_f32 v[104:105], v[104:105], v[172:173]
	s_waitcnt vmcnt(2)
	v_pk_add_f32 v[102:103], v[102:103], v[178:179]
	v_pk_add_f32 v[100:101], v[100:101], v[176:177]
	s_waitcnt vmcnt(1)
	v_pk_add_f32 v[98:99], v[98:99], v[182:183]
	v_pk_add_f32 v[96:97], v[96:97], v[180:181]
	global_store_dwordx4 v[144:145], v[124:127], off
	global_store_dwordx4 v[144:145], v[120:123], off offset:64
	global_store_dwordx4 v[144:145], v[116:119], off offset:512
	global_store_dwordx4 v[112:113], v[108:111], off
	global_store_dwordx4 v[112:113], v[104:107], off offset:64
	global_store_dwordx4 v[112:113], v[100:103], off offset:512
	global_store_dwordx4 v[112:113], v[96:99], off offset:576
	s_nop 1
	v_or_b32_e32 v96, 32, v184
	v_or_b32_e32 v112, 48, v184
	v_ashrrev_i32_e32 v97, 31, v96
	v_ashrrev_i32_e32 v113, 31, v112
	v_lshlrev_b64 v[144:145], 12, v[96:97]
	v_lshlrev_b64 v[146:147], 12, v[112:113]
	v_lshl_add_u64 v[108:109], v[136:137], 0, v[144:145]
	v_lshl_add_u64 v[124:125], v[136:137], 0, v[146:147]
	global_load_dwordx4 v[96:99], v[108:109], off
	global_load_dwordx4 v[100:103], v[108:109], off offset:64
	global_load_dwordx4 v[104:107], v[108:109], off offset:512
	s_nop 0
	global_load_dwordx4 v[108:111], v[108:109], off offset:576
	s_nop 0
	global_load_dwordx4 v[112:115], v[124:125], off
	global_load_dwordx4 v[116:119], v[124:125], off offset:64
	global_load_dwordx4 v[120:123], v[124:125], off offset:512
	s_nop 0
	global_load_dwordx4 v[124:127], v[124:125], off offset:576
	s_waitcnt vmcnt(7)
	v_pk_add_f32 v[92:93], v[92:93], v[96:97]
	v_lshl_add_u64 v[96:97], s[2:3], 0, v[144:145]
	v_lshl_add_u64 v[96:97], v[96:97], 0, v[134:135]
	s_waitcnt vmcnt(4)
	v_pk_add_f32 v[82:83], v[82:83], v[110:111]
	v_pk_add_f32 v[80:81], v[80:81], v[108:109]
	global_store_dwordx4 v[96:97], v[80:83], off offset:576
	v_pk_add_f32 v[94:95], v[94:95], v[98:99]
	v_pk_add_f32 v[90:91], v[90:91], v[102:103]
	v_lshl_add_u64 v[80:81], s[2:3], 0, v[146:147]
	v_pk_add_f32 v[88:89], v[88:89], v[100:101]
	v_pk_add_f32 v[86:87], v[86:87], v[106:107]
	v_pk_add_f32 v[84:85], v[84:85], v[104:105]
	s_waitcnt vmcnt(4)
	v_pk_add_f32 v[78:79], v[78:79], v[114:115]
	v_pk_add_f32 v[76:77], v[76:77], v[112:113]
	v_lshl_add_u64 v[80:81], v[80:81], 0, v[134:135]
	s_waitcnt vmcnt(3)
	v_pk_add_f32 v[74:75], v[74:75], v[118:119]
	v_pk_add_f32 v[72:73], v[72:73], v[116:117]
	s_waitcnt vmcnt(2)
	v_pk_add_f32 v[70:71], v[70:71], v[122:123]
	v_pk_add_f32 v[68:69], v[68:69], v[120:121]
	s_waitcnt vmcnt(1)
; #define PG8_BAR __builtin_amdgcn_s_barrier()
; template <class Epi, class Sched, bool ALIGN_EPI = false, bool SP2 = false>
; __device__ __forceinline__ void gemm_phase(PG8_LAS unsigned char* lds, const Gemm g, const Sched& S, const Epi& E) {
;     ...
;         if constexpr (ALIGN_EPI) { if (wr == 0) PG8_BAR; }
;         if constexpr (!Epi::AFTER_DRAIN) { E(acc, cur, wr, wc, fr, fq); S.done(cur); }
;         if (!has_next) break;
; #pragma unroll
;         for (int a = 0; a < 2; ++a)
; #pragma unroll
;             for (int b = 0; b < 2; ++b)
; #pragma unroll
;                 for (int m = 0; m < 4; ++m)
; #pragma unroll
;                     for (int n = 0; n < 2; ++n) acc[a][b][m][n] = (f32x4){0.f, 0.f, 0.f, 0.f};
;         cur = nxt; cA = nA; cB = nB; ++ui;
;         if constexpr (ALIGN_EPI) { if (wr == 1) PG8_BAR; }
;     __device__ __forceinline__ void operator()(const f32x4 (&acc)[2][2][4][2], const pg8::Unit& u, int wr, int wc, int fr, int fq) const {
;     ...
;         for (int ai = 0; ai < 2; ++ai)
; #pragma unroll
;             for (int mh = 0; mh < 2; ++mh) {
;                 f32x4 xi[2][2][2];
; #pragma unroll
;                 for (int m = 0; m < 2; ++m)
; #pragma unroll
;                     for (int bj = 0; bj < 2; ++bj)
; #pragma unroll
;                         for (int n = 0; n < 2; ++n) xi[m][bj][n] = *(const f32x4*)(Xin + (size_t)(row0 + ai * 128 + (2 * mh + m) * 16) * D + col0 + bj * 128 + n * 16);
;                 __builtin_amdgcn_sched_barrier(0);
; #pragma unroll
;                 for (int m = 0; m < 2; ++m)
; #pragma unroll
;                     for (int bj = 0; bj < 2; ++bj)
; #pragma unroll
;                         for (int n = 0; n < 2; ++n) *(f32x4*)(Xout + (size_t)(row0 + ai * 128 + (2 * mh + m) * 16) * D + col0 + bj * 128 + n * 16) = xi[m][bj][n] + acc[ai][bj][2 * mh + m][n] * scale;
;                 __builtin_amdgcn_sched_barrier(0);
;             }
	v_pk_add_f32 v[66:67], v[66:67], v[126:127]
	v_pk_add_f32 v[64:65], v[64:65], v[124:125]
	global_store_dwordx4 v[96:97], v[92:95], off
	global_store_dwordx4 v[96:97], v[88:91], off offset:64
	global_store_dwordx4 v[96:97], v[84:87], off offset:512
	global_store_dwordx4 v[80:81], v[76:79], off
	global_store_dwordx4 v[80:81], v[72:75], off offset:64
	global_store_dwordx4 v[80:81], v[68:71], off offset:512
	global_store_dwordx4 v[80:81], v[64:67], off offset:576
	s_mov_b64 s[0:1], 0x80000
	v_lshl_add_u64 v[96:97], v[138:139], 0, s[0:1]
	s_mov_b64 s[0:1], 0x90000
	v_lshl_add_u64 v[98:99], v[138:139], 0, s[0:1]
	v_lshl_add_u64 v[76:77], v[136:137], 0, v[96:97]
	v_lshl_add_u64 v[92:93], v[136:137], 0, v[98:99]
	global_load_dwordx4 v[64:67], v[76:77], off
	global_load_dwordx4 v[68:71], v[76:77], off offset:64
	global_load_dwordx4 v[72:75], v[76:77], off offset:512
	s_nop 0
	global_load_dwordx4 v[76:79], v[76:77], off offset:576
	s_nop 0
	global_load_dwordx4 v[80:83], v[92:93], off
	global_load_dwordx4 v[84:87], v[92:93], off offset:64
	global_load_dwordx4 v[88:91], v[92:93], off offset:512
	s_nop 0
	global_load_dwordx4 v[92:95], v[92:93], off offset:576
	s_waitcnt vmcnt(7)
	v_pk_add_f32 v[60:61], v[60:61], v[64:65]
	v_lshl_add_u64 v[64:65], s[2:3], 0, v[96:97]
	v_lshl_add_u64 v[64:65], v[64:65], 0, v[134:135]
	s_waitcnt vmcnt(4)
	v_pk_add_f32 v[50:51], v[50:51], v[78:79]
	v_pk_add_f32 v[48:49], v[48:49], v[76:77]
	global_store_dwordx4 v[64:65], v[48:51], off offset:576
	v_pk_add_f32 v[62:63], v[62:63], v[66:67]
	v_pk_add_f32 v[58:59], v[58:59], v[70:71]
	v_lshl_add_u64 v[48:49], s[2:3], 0, v[98:99]
	v_pk_add_f32 v[56:57], v[56:57], v[68:69]
	v_pk_add_f32 v[54:55], v[54:55], v[74:75]
	v_pk_add_f32 v[52:53], v[52:53], v[72:73]
	s_waitcnt vmcnt(4)
	v_pk_add_f32 v[46:47], v[46:47], v[82:83]
	v_pk_add_f32 v[44:45], v[44:45], v[80:81]
	v_lshl_add_u64 v[48:49], v[48:49], 0, v[134:135]
	s_waitcnt vmcnt(3)
	v_pk_add_f32 v[42:43], v[42:43], v[86:87]
	v_pk_add_f32 v[40:41], v[40:41], v[84:85]
	s_waitcnt vmcnt(2)
	v_pk_add_f32 v[38:39], v[38:39], v[90:91]
	v_pk_add_f32 v[36:37], v[36:37], v[88:89]
	s_waitcnt vmcnt(1)
	v_pk_add_f32 v[34:35], v[34:35], v[94:95]
	v_pk_add_f32 v[32:33], v[32:33], v[92:93]
	global_store_dwordx4 v[64:65], v[60:63], off
	global_store_dwordx4 v[64:65], v[56:59], off offset:64
	global_store_dwordx4 v[64:65], v[52:55], off offset:512
	global_store_dwordx4 v[48:49], v[44:47], off
	global_store_dwordx4 v[48:49], v[40:43], off offset:64
	global_store_dwordx4 v[48:49], v[36:39], off offset:512
	global_store_dwordx4 v[48:49], v[32:35], off offset:576
	s_mov_b64 s[0:1], 0xa0000
	v_lshl_add_u64 v[64:65], v[138:139], 0, s[0:1]
	s_mov_b64 s[0:1], 0xb0000
	v_lshl_add_u64 v[66:67], v[138:139], 0, s[0:1]
	v_lshl_add_u64 v[44:45], v[136:137], 0, v[64:65]
	v_lshl_add_u64 v[60:61], v[136:137], 0, v[66:67]
	global_load_dwordx4 v[32:35], v[44:45], off
	global_load_dwordx4 v[36:39], v[44:45], off offset:64
	global_load_dwordx4 v[40:43], v[44:45], off offset:512
	s_nop 0
	global_load_dwordx4 v[44:47], v[44:45], off offset:576
	s_nop 0
	global_load_dwordx4 v[48:51], v[60:61], off
	global_load_dwordx4 v[52:55], v[60:61], off offset:64
	global_load_dwordx4 v[56:59], v[60:61], off offset:512
	s_nop 0
	global_load_dwordx4 v[60:63], v[60:61], off offset:576
	s_waitcnt vmcnt(7)
	v_pk_add_f32 v[28:29], v[28:29], v[32:33]
	v_lshl_add_u64 v[32:33], s[2:3], 0, v[64:65]
	v_lshl_add_u64 v[32:33], v[32:33], 0, v[134:135]
	s_waitcnt vmcnt(4)
	v_pk_add_f32 v[18:19], v[18:19], v[46:47]
	v_pk_add_f32 v[16:17], v[16:17], v[44:45]
	global_store_dwordx4 v[32:33], v[16:19], off offset:576
	v_pk_add_f32 v[30:31], v[30:31], v[34:35]
	v_pk_add_f32 v[26:27], v[26:27], v[38:39]
	v_lshl_add_u64 v[16:17], s[2:3], 0, v[66:67]
	v_pk_add_f32 v[24:25], v[24:25], v[36:37]
	v_pk_add_f32 v[22:23], v[22:23], v[42:43]
	v_pk_add_f32 v[20:21], v[20:21], v[40:41]
	s_waitcnt vmcnt(4)
	v_pk_add_f32 v[14:15], v[14:15], v[50:51]
	v_pk_add_f32 v[12:13], v[12:13], v[48:49]
	v_lshl_add_u64 v[16:17], v[16:17], 0, v[134:135]
	s_waitcnt vmcnt(3)
	v_pk_add_f32 v[10:11], v[10:11], v[54:55]
	v_pk_add_f32 v[8:9], v[8:9], v[52:53]
	s_waitcnt vmcnt(2)
	v_pk_add_f32 v[6:7], v[6:7], v[58:59]
	v_pk_add_f32 v[4:5], v[4:5], v[56:57]
	s_waitcnt vmcnt(1)
	v_pk_add_f32 v[2:3], v[2:3], v[62:63]
	v_pk_add_f32 v[0:1], v[0:1], v[60:61]
	global_store_dwordx4 v[32:33], v[28:31], off
	global_store_dwordx4 v[32:33], v[24:27], off offset:64
	global_store_dwordx4 v[32:33], v[20:23], off offset:512
	global_store_dwordx4 v[16:17], v[12:15], off
	global_store_dwordx4 v[16:17], v[8:11], off offset:64
	global_store_dwordx4 v[16:17], v[4:7], off offset:512
	global_store_dwordx4 v[16:17], v[0:3], off offset:576
	s_and_b64 vcc, exec, s[4:5]
	s_mov_b64 s[0:1], -1
	s_cbranch_vccnz .LBB0_145
	s_andn2_b64 vcc, exec, s[16:17]
	s_cbranch_vccnz .LBB0_144
	s_barrier
	s_branch .LBB0_144

;     __device__ __forceinline__ void operator()(const f32x4 (&acc)[2][2][4][2], const pg8::Unit& u, int wr, int wc, int fr, int fq) const {
;         const int row0 = u.pm * 256 + wr * 64 + fr, col0 = u.pn * 256 + wc * 32 + 4 * fq;
; #pragma unroll
;         for (int ai = 0; ai < 2; ++ai)
; #pragma unroll
;             for (int mh = 0; mh < 2; ++mh) {
;                 f32x4 xi[2][2][2];
; #pragma unroll
;                 for (int m = 0; m < 2; ++m)
; #pragma unroll
;                     for (int bj = 0; bj < 2; ++bj)
; #pragma unroll
;                         for (int n = 0; n < 2; ++n) xi[m][bj][n] = *(const f32x4*)(Xin + (size_t)(row0 + ai * 128 + (2 * mh + m) * 16) * D + col0 + bj * 128 + n * 16);
;                 __builtin_amdgcn_sched_barrier(0);
; #pragma unroll
;                 for (int m = 0; m < 2; ++m)
; #pragma unroll
;                     for (int bj = 0; bj < 2; ++bj)
; #pragma unroll
;                         for (int n = 0; n < 2; ++n) *(f32x4*)(Xout + (size_t)(row0 + ai * 128 + (2 * mh + m) * 16) * D + col0 + bj * 128 + n * 16) = xi[m][bj][n] + acc[ai][bj][2 * mh + m][n] * scale;
.LBB0_817:
	v_lshl_or_b32 v16, s34, 8, v148
	v_lshl_add_u32 v26, s35, 8, v146
	v_ashrrev_i32_e32 v17, 31, v16
	v_lshlrev_b64 v[16:17], 2, v[16:17]
	v_ashrrev_i32_e32 v27, 31, v26
	v_lshl_add_u64 v[18:19], s[12:13], 0, v[16:17]
	v_lshlrev_b64 v[24:25], 12, v[26:27]
	v_lshl_add_u64 v[150:151], v[18:19], 0, v[24:25]
	global_load_dwordx4 v[40:43], v[150:151], off
	global_load_dwordx4 v[168:171], v[150:151], off offset:64
	global_load_dwordx4 v[172:175], v[150:151], off offset:512
	global_load_dwordx4 v[176:179], v[150:151], off offset:576
	v_or_b32_e32 v150, 16, v26
	v_ashrrev_i32_e32 v151, 31, v150
	v_lshlrev_b64 v[150:151], 12, v[150:151]
	v_lshl_add_u64 v[158:159], v[18:19], 0, v[150:151]
	global_load_dwordx4 v[180:183], v[158:159], off
	global_load_dwordx4 v[184:187], v[158:159], off offset:64
	global_load_dwordx4 v[188:191], v[158:159], off offset:512
	global_load_dwordx4 v[192:195], v[158:159], off offset:576
	v_readlane_b32 s2, v254, 52
	v_readlane_b32 s3, v254, 53
	s_waitcnt vmcnt(7)
	v_pk_add_f32 v[42:43], v[134:135], v[42:43]
	v_pk_add_f32 v[40:41], v[136:137], v[40:41]
	v_lshl_add_u64 v[134:135], s[2:3], 0, v[24:25]
	v_lshl_add_u64 v[134:135], v[134:135], 0, v[16:17]
	global_store_dwordx4 v[134:135], v[40:43], off
	s_nop 1
	s_waitcnt vmcnt(7)
	v_pk_add_f32 v[42:43], v[126:127], v[170:171]
	v_pk_add_f32 v[40:41], v[124:125], v[168:169]
	global_store_dwordx4 v[134:135], v[40:43], off offset:64
	s_nop 1
	s_waitcnt vmcnt(7)
	v_pk_add_f32 v[42:43], v[144:145], v[174:175]
	v_pk_add_f32 v[40:41], v[142:143], v[172:173]
	global_store_dwordx4 v[134:135], v[40:43], off offset:512
	s_nop 1
	s_waitcnt vmcnt(7)
	v_pk_add_f32 v[42:43], v[140:141], v[178:179]
	v_pk_add_f32 v[40:41], v[138:139], v[176:177]
	global_store_dwordx4 v[134:135], v[40:43], off offset:576
	s_nop 1
	s_waitcnt vmcnt(7)
	v_pk_add_f32 v[40:41], v[116:117], v[180:181]
	v_lshl_add_u64 v[116:117], s[2:3], 0, v[150:151]
	v_pk_add_f32 v[42:43], v[118:119], v[182:183]
	v_lshl_add_u64 v[116:117], v[116:117], 0, v[16:17]
	global_store_dwordx4 v[116:117], v[40:43], off
	s_nop 1
	s_waitcnt vmcnt(7)
	v_pk_add_f32 v[42:43], v[110:111], v[186:187]
	v_pk_add_f32 v[40:41], v[108:109], v[184:185]
	global_store_dwordx4 v[116:117], v[40:43], off offset:64
	s_nop 1
	s_waitcnt vmcnt(7)
	v_pk_add_f32 v[42:43], v[122:123], v[190:191]
	v_pk_add_f32 v[40:41], v[120:121], v[188:189]
	global_store_dwordx4 v[116:117], v[40:43], off offset:512
	s_nop 1
	s_waitcnt vmcnt(7)
	v_pk_add_f32 v[42:43], v[114:115], v[194:195]
	v_pk_add_f32 v[40:41], v[112:113], v[192:193]
	global_store_dwordx4 v[116:117], v[40:43], off offset:576
	s_nop 1
	v_or_b32_e32 v40, 32, v26
	v_or_b32_e32 v26, 48, v26
	v_ashrrev_i32_e32 v41, 31, v40
	v_ashrrev_i32_e32 v27, 31, v26
	v_lshlrev_b64 v[142:143], 12, v[40:41]
	v_lshlrev_b64 v[26:27], 12, v[26:27]
	v_lshl_add_u64 v[116:117], v[18:19], 0, v[142:143]
	v_lshl_add_u64 v[138:139], v[18:19], 0, v[26:27]
	global_load_dwordx4 v[40:43], v[116:117], off
	global_load_dwordx4 v[108:111], v[116:117], off offset:64
	global_load_dwordx4 v[112:115], v[116:117], off offset:512
	s_nop 0
	global_load_dwordx4 v[116:119], v[116:117], off offset:576
	s_nop 0
	global_load_dwordx4 v[120:123], v[138:139], off
	global_load_dwordx4 v[124:127], v[138:139], off offset:64
	global_load_dwordx4 v[134:137], v[138:139], off offset:512
	s_nop 0
	global_load_dwordx4 v[138:141], v[138:139], off offset:576
	s_waitcnt vmcnt(7)
	v_pk_add_f32 v[40:41], v[100:101], v[40:41]
	v_lshl_add_u64 v[100:101], s[2:3], 0, v[142:143]
	v_pk_add_f32 v[42:43], v[102:103], v[42:43]
	v_lshl_add_u64 v[100:101], v[100:101], 0, v[16:17]
	global_store_dwordx4 v[100:101], v[40:43], off
	v_lshl_add_u64 v[26:27], s[2:3], 0, v[26:27]
	v_lshl_add_u64 v[26:27], v[26:27], 0, v[16:17]
	s_waitcnt vmcnt(7)
	v_pk_add_f32 v[42:43], v[94:95], v[110:111]
	v_pk_add_f32 v[40:41], v[92:93], v[108:109]
	global_store_dwordx4 v[100:101], v[40:43], off offset:64
	s_nop 1
	s_waitcnt vmcnt(7)
	v_pk_add_f32 v[42:43], v[106:107], v[114:115]
	v_pk_add_f32 v[40:41], v[104:105], v[112:113]
	global_store_dwordx4 v[100:101], v[40:43], off offset:512
	s_nop 1
	s_waitcnt vmcnt(7)
	v_pk_add_f32 v[42:43], v[98:99], v[118:119]
	v_pk_add_f32 v[40:41], v[96:97], v[116:117]
	global_store_dwordx4 v[100:101], v[40:43], off offset:576
	s_nop 1
	s_waitcnt vmcnt(7)
	v_pk_add_f32 v[42:43], v[86:87], v[122:123]
	v_pk_add_f32 v[40:41], v[84:85], v[120:121]
	global_store_dwordx4 v[26:27], v[40:43], off
	s_nop 1
	s_waitcnt vmcnt(7)
	v_pk_add_f32 v[42:43], v[74:75], v[126:127]
	v_pk_add_f32 v[40:41], v[72:73], v[124:125]
	global_store_dwordx4 v[26:27], v[40:43], off offset:64
	s_nop 1
	s_waitcnt vmcnt(7)
	v_pk_add_f32 v[42:43], v[90:91], v[136:137]
	v_pk_add_f32 v[40:41], v[88:89], v[134:135]
	global_store_dwordx4 v[26:27], v[40:43], off offset:512
	s_nop 1
	s_waitcnt vmcnt(7)
; #define PG8_BAR __builtin_amdgcn_s_barrier()
; template <class Epi, class Sched, bool ALIGN_EPI = false, bool SP2 = false>
; __device__ __forceinline__ void gemm_phase(PG8_LAS unsigned char* lds, const Gemm g, const Sched& S, const Epi& E) {
;     ...
;         if constexpr (ALIGN_EPI) { if (wr == 0) PG8_BAR; }
;         if constexpr (!Epi::AFTER_DRAIN) { E(acc, cur, wr, wc, fr, fq); S.done(cur); }
;         if (!has_next) break;
; #pragma unroll
;         for (int a = 0; a < 2; ++a)
; #pragma unroll
;             for (int b = 0; b < 2; ++b)
; #pragma unroll
;                 for (int m = 0; m < 4; ++m)
; #pragma unroll
;                     for (int n = 0; n < 2; ++n) acc[a][b][m][n] = (f32x4){0.f, 0.f, 0.f, 0.f};
;         cur = nxt; cA = nA; cB = nB; ++ui;
;         if constexpr (ALIGN_EPI) { if (wr == 1) PG8_BAR; }
;     __device__ __forceinline__ void operator()(const f32x4 (&acc)[2][2][4][2], const pg8::Unit& u, int wr, int wc, int fr, int fq) const {
;     ...
;         for (int ai = 0; ai < 2; ++ai)
; #pragma unroll
;             for (int mh = 0; mh < 2; ++mh) {
;                 f32x4 xi[2][2][2];
; #pragma unroll
;                 for (int m = 0; m < 2; ++m)
; #pragma unroll
;                     for (int bj = 0; bj < 2; ++bj)
; #pragma unroll
;                         for (int n = 0; n < 2; ++n) xi[m][bj][n] = *(const f32x4*)(Xin + (size_t)(row0 + ai * 128 + (2 * mh + m) * 16) * D + col0 + bj * 128 + n * 16);
;                 __builtin_amdgcn_sched_barrier(0);
; #pragma unroll
;                 for (int m = 0; m < 2; ++m)
; #pragma unroll
;                     for (int bj = 0; bj < 2; ++bj)
; #pragma unroll
;                         for (int n = 0; n < 2; ++n) *(f32x4*)(Xout + (size_t)(row0 + ai * 128 + (2 * mh + m) * 16) * D + col0 + bj * 128 + n * 16) = xi[m][bj][n] + acc[ai][bj][2 * mh + m][n] * scale;
;                 __builtin_amdgcn_sched_barrier(0);
;             }
	v_pk_add_f32 v[42:43], v[82:83], v[140:141]
	v_pk_add_f32 v[40:41], v[80:81], v[138:139]
	global_store_dwordx4 v[26:27], v[40:43], off offset:576
	s_mov_b64 s[0:1], 0x80000
	v_lshl_add_u64 v[26:27], v[24:25], 0, s[0:1]
	s_mov_b64 s[0:1], 0x90000
	v_lshl_add_u64 v[104:105], v[24:25], 0, s[0:1]
	v_lshl_add_u64 v[84:85], v[18:19], 0, v[26:27]
	v_lshl_add_u64 v[100:101], v[18:19], 0, v[104:105]
	global_load_dwordx4 v[40:43], v[84:85], off
	global_load_dwordx4 v[72:75], v[84:85], off offset:64
	global_load_dwordx4 v[80:83], v[84:85], off offset:512
	s_nop 0
	global_load_dwordx4 v[84:87], v[84:85], off offset:576
	s_nop 0
	global_load_dwordx4 v[88:91], v[100:101], off
	global_load_dwordx4 v[92:95], v[100:101], off offset:64
	global_load_dwordx4 v[96:99], v[100:101], off offset:512
	s_nop 0
	global_load_dwordx4 v[100:103], v[100:101], off offset:576
	v_lshl_add_u64 v[26:27], s[2:3], 0, v[26:27]
	s_waitcnt vmcnt(7)
	v_pk_add_f32 v[42:43], v[66:67], v[42:43]
	v_pk_add_f32 v[40:41], v[64:65], v[40:41]
	v_lshl_add_u64 v[26:27], v[26:27], 0, v[16:17]
	global_store_dwordx4 v[26:27], v[40:43], off
	s_nop 1
	s_waitcnt vmcnt(7)
	v_pk_add_f32 v[42:43], v[62:63], v[74:75]
	v_pk_add_f32 v[40:41], v[60:61], v[72:73]
	global_store_dwordx4 v[26:27], v[40:43], off offset:64
	s_nop 1
	s_waitcnt vmcnt(7)
	v_pk_add_f32 v[42:43], v[78:79], v[82:83]
	v_pk_add_f32 v[40:41], v[76:77], v[80:81]
	global_store_dwordx4 v[26:27], v[40:43], off offset:512
	s_nop 1
	s_waitcnt vmcnt(7)
	v_pk_add_f32 v[42:43], v[70:71], v[86:87]
	v_pk_add_f32 v[40:41], v[68:69], v[84:85]
	global_store_dwordx4 v[26:27], v[40:43], off offset:576
	v_lshl_add_u64 v[26:27], s[2:3], 0, v[104:105]
	v_lshl_add_u64 v[26:27], v[26:27], 0, v[16:17]
	s_waitcnt vmcnt(7)
	v_pk_add_f32 v[42:43], v[54:55], v[90:91]
	v_pk_add_f32 v[40:41], v[52:53], v[88:89]
	global_store_dwordx4 v[26:27], v[40:43], off
	s_nop 1
	s_waitcnt vmcnt(7)
	v_pk_add_f32 v[42:43], v[46:47], v[94:95]
	v_pk_add_f32 v[40:41], v[44:45], v[92:93]
	global_store_dwordx4 v[26:27], v[40:43], off offset:64
	s_nop 1
	s_waitcnt vmcnt(7)
	v_pk_add_f32 v[42:43], v[58:59], v[98:99]
	v_pk_add_f32 v[40:41], v[56:57], v[96:97]
	global_store_dwordx4 v[26:27], v[40:43], off offset:512
	s_nop 1
	s_waitcnt vmcnt(7)
	v_pk_add_f32 v[42:43], v[50:51], v[102:103]
	v_pk_add_f32 v[40:41], v[48:49], v[100:101]
	global_store_dwordx4 v[26:27], v[40:43], off offset:576
	s_mov_b64 s[0:1], 0xa0000
	v_lshl_add_u64 v[68:69], v[24:25], 0, s[0:1]
	s_mov_b64 s[0:1], 0xb0000
	v_lshl_add_u64 v[70:71], v[24:25], 0, s[0:1]
	v_lshl_add_u64 v[26:27], v[18:19], 0, v[68:69]
	v_lshl_add_u64 v[18:19], v[18:19], 0, v[70:71]
	global_load_dwordx4 v[40:43], v[26:27], off
	global_load_dwordx4 v[44:47], v[26:27], off offset:64
	global_load_dwordx4 v[48:51], v[26:27], off offset:512
	global_load_dwordx4 v[52:55], v[26:27], off offset:576
	s_nop 0
	global_load_dwordx4 v[24:27], v[18:19], off
	global_load_dwordx4 v[56:59], v[18:19], off offset:64
	global_load_dwordx4 v[60:63], v[18:19], off offset:512
	global_load_dwordx4 v[64:67], v[18:19], off offset:576
	v_lshl_add_u64 v[18:19], s[2:3], 0, v[68:69]
	s_waitcnt vmcnt(7)
	v_pk_add_f32 v[28:29], v[28:29], v[40:41]
	v_lshl_add_u64 v[40:41], v[18:19], 0, v[16:17]
	s_waitcnt vmcnt(6)
	v_pk_add_f32 v[22:23], v[22:23], v[46:47]
	v_pk_add_f32 v[20:21], v[20:21], v[44:45]
	global_store_dwordx4 v[40:41], v[20:23], off offset:64
	s_waitcnt vmcnt(6)
	v_pk_add_f32 v[18:19], v[36:37], v[48:49]
	v_pk_add_f32 v[30:31], v[30:31], v[42:43]
	v_pk_add_f32 v[20:21], v[38:39], v[50:51]
	global_store_dwordx4 v[40:41], v[18:21], off offset:512
	s_waitcnt vmcnt(5)
	v_pk_add_f32 v[14:15], v[14:15], v[26:27]
	v_pk_add_f32 v[12:13], v[12:13], v[24:25]
	v_pk_add_f32 v[20:21], v[34:35], v[54:55]
	v_pk_add_f32 v[18:19], v[32:33], v[52:53]
	global_store_dwordx4 v[40:41], v[18:21], off offset:576
	s_waitcnt vmcnt(5)
	v_pk_add_f32 v[10:11], v[10:11], v[58:59]
	v_pk_add_f32 v[8:9], v[8:9], v[56:57]
	v_lshl_add_u64 v[18:19], s[2:3], 0, v[70:71]
	v_lshl_add_u64 v[16:17], v[18:19], 0, v[16:17]
	s_waitcnt vmcnt(4)
	v_pk_add_f32 v[6:7], v[6:7], v[62:63]
	v_pk_add_f32 v[4:5], v[4:5], v[60:61]
	s_waitcnt vmcnt(3)
	v_pk_add_f32 v[2:3], v[2:3], v[66:67]
	v_pk_add_f32 v[0:1], v[0:1], v[64:65]
	global_store_dwordx4 v[40:41], v[28:31], off
	global_store_dwordx4 v[16:17], v[12:15], off
	global_store_dwordx4 v[16:17], v[8:11], off offset:64
	global_store_dwordx4 v[16:17], v[4:7], off offset:512
	global_store_dwordx4 v[16:17], v[0:3], off offset:576
	s_and_b64 vcc, exec, s[4:5]
	s_mov_b64 s[0:1], -1
	s_cbranch_vccnz .LBB0_800
	s_andn2_b64 vcc, exec, s[16:17]
	s_cbranch_vccnz .LBB0_799
	s_barrier
	s_branch .LBB0_799
